# LN1-phase p f32->f16 conversion loop software-pipelined like the x loop
# baseline (speedup 1.0000x reference)
; __device__ __forceinline__ void cvt_pass(const float* src, h16* dst, size_t n, float* dup) {
;     for (size_t i = ((size_t)blockIdx.x * 512 + threadIdx.x) * 8; i < n; i += (size_t)gridDim.x * 512 * 8) {
;         const f32x4 a = *(const f32x4*)(src + i), b = *(const f32x4*)(src + i + 4);
;         h16x8 o; o[0] = (h16)a.x; o[1] = (h16)a.y; o[2] = (h16)a.z; o[3] = (h16)a.w; o[4] = (h16)b.x; o[5] = (h16)b.y; o[6] = (h16)b.z; o[7] = (h16)b.w;
;         *(h16x8*)(dst + i) = o;
;         if (dup) { *(f32x4*)(dup + i) = a; *(f32x4*)(dup + i + 4) = b; }
;     }
; }
; __global__ void __launch_bounds__(512, 2) fwd_megakernel(Params P) {
;     ...
;                 if (kind == K_LN1) cvt_pass(PK->p + (size_t)i * NTOK * 256, P16, (size_t)NTOK * 256, nullptr);
.LBB0_1082:
	s_mov_b64 s[10:11], 0x7fffff
	global_load_dwordx4 v[6:9], v[2:3], off
	global_load_dwordx4 v[10:13], v[2:3], off offset:-16
.Lcvp_loop:
	s_mov_b64 s[98:99], exec
	v_lshl_add_u64 v[4:5], v[4:5], 0, s[92:93]
	v_cmp_lt_u64_e32 vcc, s[10:11], v[4:5]
	v_lshl_add_u64 v[2:3], v[2:3], 0, s[56:57]
	s_or_b64 s[4:5], vcc, s[4:5]
	s_andn2_b64 exec, s[98:99], s[4:5]
	s_cbranch_execz .Lcvp_last0
	global_load_dwordx4 v[14:17], v[2:3], off
	global_load_dwordx4 v[18:21], v[2:3], off offset:-16
	s_mov_b64 exec, s[98:99]
	s_waitcnt vmcnt(2)
	v_cvt_pk_f16_f32 v9, v8, v9
	v_cvt_pk_f16_f32 v8, v6, v7
	v_cvt_pk_f16_f32 v7, v12, v13
	v_cvt_pk_f16_f32 v6, v10, v11
	global_store_dwordx4 v[0:1], v[6:9], off
	v_lshl_add_u64 v[0:1], v[0:1], 0, s[58:59]
	s_andn2_b64 exec, exec, s[4:5]
	s_mov_b64 s[98:99], exec
	v_lshl_add_u64 v[4:5], v[4:5], 0, s[92:93]
	v_cmp_lt_u64_e32 vcc, s[10:11], v[4:5]
	v_lshl_add_u64 v[2:3], v[2:3], 0, s[56:57]
	s_or_b64 s[4:5], vcc, s[4:5]
	s_andn2_b64 exec, s[98:99], s[4:5]
	s_cbranch_execz .Lcvp_last1
	global_load_dwordx4 v[6:9], v[2:3], off
	global_load_dwordx4 v[10:13], v[2:3], off offset:-16
	s_mov_b64 exec, s[98:99]
	s_waitcnt vmcnt(2)
	v_cvt_pk_f16_f32 v17, v16, v17
	v_cvt_pk_f16_f32 v16, v14, v15
	v_cvt_pk_f16_f32 v15, v20, v21
	v_cvt_pk_f16_f32 v14, v18, v19
	global_store_dwordx4 v[0:1], v[14:17], off
	v_lshl_add_u64 v[0:1], v[0:1], 0, s[58:59]
	s_andn2_b64 exec, exec, s[4:5]
	s_branch .Lcvp_loop
.Lcvp_last0:
	s_mov_b64 exec, s[98:99]
	s_waitcnt vmcnt(0)
	v_cvt_pk_f16_f32 v9, v8, v9
	v_cvt_pk_f16_f32 v8, v6, v7
	v_cvt_pk_f16_f32 v7, v12, v13
	v_cvt_pk_f16_f32 v6, v10, v11
	global_store_dwordx4 v[0:1], v[6:9], off
	v_lshl_add_u64 v[0:1], v[0:1], 0, s[58:59]
	s_branch .LBB0_1083
.Lcvp_last1:
	s_mov_b64 exec, s[98:99]
	s_waitcnt vmcnt(0)
	v_cvt_pk_f16_f32 v17, v16, v17
	v_cvt_pk_f16_f32 v16, v14, v15
	v_cvt_pk_f16_f32 v15, v20, v21
	v_cvt_pk_f16_f32 v14, v18, v19
	global_store_dwordx4 v[0:1], v[14:17], off
	v_lshl_add_u64 v[0:1], v[0:1], 0, s[58:59]
